# half-unit tail round for the gate/up GEMM phases (last partial round split into 128-row half-units over all workgroups)
# speedup vs baseline: 1.0015x; 1.0015x over previous
.LBB0_156:
	s_andn2_b64 vcc, exec, s[22:23]
	s_cbranch_vccnz .LBB0_228
	s_mov_b32 s100, 0
	s_mov_b32 s101, 0
	s_waitcnt lgkmcnt(0)
	v_bfe_i32 v3, v14, 27, 1
	v_lshlrev_b32_e32 v1, 4, v14
	v_lshrrev_b32_e32 v3, 22, v3
	v_add_u32_e32 v3, v1, v3
	v_and_b32_e32 v3, 0xfffffc00, v3
	v_ashrrev_i32_e32 v2, 31, v14
	v_sub_u32_e32 v3, v1, v3
	v_lshrrev_b32_e32 v2, 26, v2
	v_lshrrev_b32_e32 v4, 4, v3
	v_add_u32_e32 v2, v14, v2
	v_bitop3_b32 v4, v4, v3, 32 bitop3:0x6c
	v_ashrrev_i32_e32 v3, 31, v3
	v_ashrrev_i32_e32 v2, 6, v2
	v_lshrrev_b32_e32 v3, 26, v3
	v_lshlrev_b32_e32 v5, 3, v2
	v_add_u32_e32 v3, v4, v3
	v_and_b32_e32 v5, -16, v5
	v_ashrrev_i32_e32 v3, 6, v3
	v_lshlrev_b32_e32 v2, 5, v2
	v_add_u32_e32 v5, v3, v5
	v_and_b32_e32 v15, 32, v2
	v_mul_i32_i24_e32 v2, 64, v3
	v_sub_u32_e32 v2, v4, v2
	v_lshlrev_b32_e32 v4, 1, v5
	v_lshrrev_b32_e32 v6, 2, v5
	v_and_b32_e32 v3, 3, v3
	s_mov_b32 s2, 0x7fffffe0
	v_ashrrev_i16_sdwa v2, v222, sext(v2) dst_sel:DWORD dst_unused:UNUSED_PAD src0_sel:DWORD src1_sel:BYTE_0
	v_and_b32_e32 v4, 24, v4
	v_and_b32_e32 v6, 4, v6
	v_and_or_b32 v3, v5, s2, v3
	v_bfe_i32 v16, v2, 0, 16
	v_or3_b32 v3, v3, v6, v4
	v_add_u32_e32 v2, v15, v16
	v_mul_lo_u32 v17, v5, s39
	v_mul_lo_u32 v3, v3, s38
	v_add_u32_e32 v1, 0x2000, v1
	v_add_lshl_u32 v186, v2, v17, 1
	v_add_lshl_u32 v188, v3, v2, 1
	v_ashrrev_i32_e32 v2, 31, v1
	v_lshrrev_b32_e32 v2, 22, v2
	v_add_u32_e32 v2, v1, v2
	v_ashrrev_i32_e32 v2, 10, v2
	v_mul_i32_i24_e32 v3, 0x400, v2
	v_sub_u32_e32 v1, v1, v3
	v_lshrrev_b32_e32 v3, 4, v1
	v_bitop3_b32 v1, v3, v1, 32 bitop3:0x6c
	v_ashrrev_i32_e32 v4, 31, v1
	s_lshl_b32 s16, s39, 8
	v_lshrrev_b32_e32 v4, 26, v4
	s_lshl_b64 s[62:63], s[16:17], 1
	s_ashr_i32 s21, s99, 31
	v_writelane_b32 v243, s59, 32
	v_lshlrev_b32_e32 v3, 3, v2
	v_add_u32_e32 v4, v1, v4
	s_mul_i32 s21, s62, s21
	s_mul_hi_u32 s22, s62, s99
	v_writelane_b32 v243, s56, 42
	v_and_b32_e32 v3, -16, v3
	v_ashrrev_i32_e32 v5, 6, v4
	s_add_i32 s21, s22, s21
	s_bfe_u32 s22, s39, 0x10017
	v_writelane_b32 v243, s57, 43
	s_ashr_i32 s1, s0, 6
	v_add_u32_e32 v3, v5, v3
	v_lshlrev_b32_e32 v2, 5, v2
	v_and_b32_e32 v5, 3, v5
	s_lshl_b32 s56, s38, 9
	s_mul_i32 s22, s22, s99
	v_and_b32_e32 v18, 32, v2
	v_and_b32_e32 v2, 0xc0, v4
	v_and_or_b32 v5, v3, s2, v5
	s_ashr_i32 s2, s0, 8
	s_lshl_b32 s69, s38, 8
	s_lshl_b32 s57, s1, 10
	s_add_i32 s21, s21, s22
	s_mul_i32 s23, s56, s88
	v_sub_u32_e32 v1, v1, v2
	v_lshlrev_b32_e32 v2, 1, v3
	v_lshrrev_b32_e32 v4, 2, v3
	s_mul_hi_i32 s22, s56, s88
	s_add_u32 s34, s48, s23
	v_ashrrev_i16_sdwa v1, v222, sext(v1) dst_sel:DWORD dst_unused:UNUSED_PAD src0_sel:DWORD src1_sel:BYTE_0
	v_and_b32_e32 v2, 24, v2
	v_and_b32_e32 v4, 4, v4
	s_addc_u32 s35, s49, s22
	s_add_i32 s90, s57, 0
	v_bfe_i32 v19, v1, 0, 16
	v_or3_b32 v2, v5, v4, v2
	s_add_i32 m0, s90, 0x10000
	v_add_u32_e32 v1, v18, v19
	v_mul_lo_u32 v2, v2, s38
	global_load_lds_dwordx4 v188, s[34:35]
	s_add_i32 m0, s90, 0x12000
	v_add_lshl_u32 v192, v2, v1, 1
	s_add_u32 s22, s34, s69
	global_load_lds_dwordx4 v192, s[34:35]
	s_addc_u32 s23, s35, 0
	s_add_i32 m0, s90, 0x14000
	v_mul_lo_u32 v20, v3, s39
	s_mul_i32 s39, s62, s99
	global_load_lds_dwordx4 v188, s[22:23]
	s_add_i32 m0, s90, 0x16000
	s_add_u32 s80, s54, s39
	v_mov_b32_e32 v189, v0
	v_mov_b32_e32 v193, v0
	s_addc_u32 s81, s55, s21
	s_add_i32 s60, s90, 0x2000
	v_lshl_add_u64 v[6:7], s[22:23], 0, v[188:189]
	v_lshl_add_u64 v[8:9], s[22:23], 0, v[192:193]
	global_load_lds_dwordx4 v192, s[22:23]
	s_mov_b32 m0, s90
	s_add_u32 s22, s80, s16
	v_add_lshl_u32 v190, v1, v20, 1
	global_load_lds_dwordx4 v186, s[80:81]
	s_mov_b32 m0, s60
	s_addc_u32 s23, s81, 0
	s_add_i32 s61, s90, 0x4000
	global_load_lds_dwordx4 v190, s[80:81]
	s_mov_b32 m0, s61
	s_add_i32 s71, s90, 0x6000
	global_load_lds_dwordx4 v186, s[22:23]
	s_mov_b32 m0, s71
	v_writelane_b32 v243, s47, 40
	global_load_lds_dwordx4 v190, s[22:23]
	v_writelane_b32 v243, s52, 44
	s_cmp_eq_u32 s2, 1
	v_mov_b32_e32 v187, v0
	v_writelane_b32 v243, s53, 45
	v_mov_b32_e32 v191, v0
	s_cselect_b64 s[22:23], -1, 0
	v_lshl_add_u64 v[2:3], s[34:35], 0, v[188:189]
	v_lshl_add_u64 v[4:5], s[34:35], 0, v[192:193]
	v_lshl_add_u64 v[10:11], s[80:81], 0, v[186:187]
	v_lshl_add_u64 v[12:13], s[80:81], 0, v[190:191]
	v_writelane_b32 v243, s22, 30
	s_cmp_lg_u32 s2, 1
	s_nop 0
	v_writelane_b32 v243, s23, 31
	s_cbranch_scc1 .LBB0_159
	s_barrier

.LBB0_161:
	s_andn2_b64 vcc, exec, s[34:35]
	s_mov_b32 s88, s2
	s_mov_b32 s99, s82
	s_mov_b32 s101, s100
	s_mov_b64 s[34:35], s[86:87]
	s_mov_b64 s[80:81], s[42:43]
	s_cbranch_vccz .LBB0_227
.LBB0_162:
	s_add_i32 s46, s46, 1
	v_readlane_b32 s0, v250, 60
	s_mul_i32 s0, s46, s0
	s_mul_hi_u32 s1, s46, s98
	s_add_i32 s1, s1, s0
	s_mul_i32 s0, s46, s98
	v_readlane_b32 s40, v243, 16
	s_add_u32 s40, s0, s40
	v_readlane_b32 s0, v250, 58
	s_addc_u32 s41, s1, s0
	s_mov_b32 s100, 0
	s_cmp_lg_u32 s46, 5
	s_cbranch_scc1 .Lhu_no
	s_cmp_lg_u32 s70, 0
	s_cbranch_scc1 .Lhu_no
	v_readlane_b32 s0, v243, 19
	s_cmp_eq_u32 s0, 1
	s_cbranch_scc1 .Lhu_no
	v_readlane_b32 s0, v243, 16
	s_and_b32 s1, s0, 7
	s_lshr_b32 s40, s0, 4
	s_lshl_b32 s40, s40, 3
	s_add_i32 s40, s40, s1
	s_addk_i32 s40, 0x500
	s_mov_b32 s41, 0
	s_bfe_u32 s100, s0, 0x10003
	s_add_i32 s100, s100, 1
.Lhu_no:
	v_mov_b64_e32 v[2:3], s[44:45]
	v_cmp_ge_i64_e32 vcc, s[40:41], v[2:3]
	v_cmp_lt_i64_e64 s[42:43], s[40:41], v[2:3]
	s_cbranch_vccnz .LBB0_164
	s_ashr_i32 s0, s40, 31
	s_lshr_b32 s0, s0, 29
	s_add_i32 s0, s40, s0
	s_ashr_i32 s1, s0, 3
	s_and_b32 s0, s0, -8
	s_sub_i32 s0, s40, s0
	s_lshr_b32 s2, s0, 31
	s_or_b32 s2, s28, s2
	s_mul_i32 s0, s2, s0
	s_add_i32 s0, s0, s1
	s_ashr_i32 s1, s0, 31
	v_readlane_b32 s2, v243, 38
	s_xor_b32 s1, s1, s2
	s_abs_i32 s2, s0
	v_readlane_b32 s40, v243, 34
	s_mul_hi_u32 s40, s2, s40
	s_mul_i32 s41, s40, s52
	s_sub_i32 s2, s2, s41
	s_add_i32 s41, s40, 1
	s_sub_i32 s66, s2, s52
	s_cmp_ge_u32 s2, s52
	s_cselect_b32 s40, s41, s40
	s_cselect_b32 s2, s66, s2
	s_add_i32 s41, s40, 1
	s_cmp_ge_u32 s2, s52
	s_cselect_b32 s2, s41, s40
	s_xor_b32 s2, s2, s1
	s_sub_i32 s1, s2, s1
	s_lshl_b32 s40, s1, 3
	s_sub_i32 s2, 64, s40
	s_min_i32 s41, s2, 8
	s_abs_i32 s2, s41
	v_cvt_f32_u32_e32 v2, s2
	s_sub_i32 s67, 0, s2
	s_mul_i32 s1, s1, s28
	s_sub_i32 s0, s0, s1
	v_rcp_iflag_f32_e32 v2, v2
	s_abs_i32 s66, s0
	s_xor_b32 s1, s0, s41
	s_ashr_i32 s1, s1, 31
	v_mul_f32_e32 v2, 0x4f7ffffe, v2
	v_cvt_u32_f32_e32 v2, v2
	s_nop 0
	v_readfirstlane_b32 s82, v2
	s_mul_i32 s67, s67, s82
	s_mul_hi_u32 s67, s82, s67
	s_add_i32 s82, s82, s67
	s_mul_hi_u32 s67, s66, s82
	s_mul_i32 s82, s67, s2
	s_sub_i32 s66, s66, s82
	s_add_i32 s82, s67, 1
	s_sub_i32 s86, s66, s2
	s_cmp_ge_u32 s66, s2
	s_cselect_b32 s67, s82, s67
	s_cselect_b32 s66, s86, s66
	s_add_i32 s82, s67, 1
	s_cmp_ge_u32 s66, s2
	s_cselect_b32 s2, s82, s67
	s_xor_b32 s2, s2, s1
	s_sub_i32 s2, s2, s1
	s_mul_i32 s1, s2, s41
	s_sub_i32 s0, s0, s1
	s_add_i32 s82, s0, s40
.LBB0_164:
	s_nop 0
	v_cndmask_b32_e64 v2, 0, 1, s[42:43]
	v_cmp_ne_u32_e64 s[40:41], 1, v2
	s_andn2_b64 vcc, exec, s[42:43]
	s_mov_b64 s[42:43], s[80:81]
	s_cbranch_vccnz .LBB0_166
	s_ashr_i32 s0, s82, 31
	s_mul_hi_u32 s1, s62, s82
	s_mul_i32 s0, s62, s0
	s_add_i32 s0, s1, s0
	s_mul_i32 s1, s63, s82
	s_add_i32 s0, s0, s1
	s_mul_i32 s1, s62, s82
	s_add_u32 s42, s54, s1
	s_addc_u32 s43, s55, s0
	s_cmp_eq_u32 s100, 2
	s_cselect_b32 s0, s16, 0
	s_add_u32 s42, s42, s0
	s_addc_u32 s43, s43, 0

.LBB0_169:
	s_add_i32 s0, s34, 2
	s_add_u32 s1, s80, 0x80
	s_addc_u32 s35, s81, 0
	s_add_i32 s47, 0, 0x10000
	s_cmp_eq_u32 s68, s34
	s_cselect_b32 s35, s43, s35
	s_cselect_b32 s34, s42, s1
	s_cselect_b32 s67, s87, vcc_hi
	s_cselect_b32 s66, s86, vcc_lo
	s_add_i32 s1, 0, 0x14000
	v_add_u32_e32 v142, s47, v234
	v_add_u32_e32 v158, s1, v234
	s_waitcnt lgkmcnt(0)
	ds_read_b128 v[130:133], v142
	ds_read_b128 v[134:137], v142 offset:1024
	ds_read_b128 v[138:141], v142 offset:2048
	ds_read_b128 v[142:145], v142 offset:3072
	ds_read_b128 v[146:149], v158
	ds_read_b128 v[150:153], v158 offset:1024
	ds_read_b128 v[154:157], v158 offset:2048
	ds_read_b128 v[158:161], v158 offset:3072
	v_lshl_add_u64 v[206:207], s[80:81], 0, v[194:195]
	s_add_i32 m0, s90, 0xc000
	ds_read_b128 v[162:165], v238
	ds_read_b128 v[166:169], v238 offset:1024
	ds_read_b128 v[170:173], v238 offset:2048
	ds_read_b128 v[174:177], v238 offset:3072
	ds_read_b128 v[178:181], v238 offset:4096
	ds_read_b128 v[182:185], v238 offset:5120
	ds_read_b128 v[198:201], v238 offset:6144
	ds_read_b128 v[202:205], v238 offset:7168
	global_load_lds_dwordx4 v[206:207], off
	v_lshl_add_u64 v[206:207], s[80:81], 0, v[196:197]
	s_add_i32 m0, s90, 0xe000
	s_nop 0
	global_load_lds_dwordx4 v[206:207], off
	s_waitcnt vmcnt(8)
	s_waitcnt lgkmcnt(0)
	s_barrier
	s_setprio 1
	s_waitcnt lgkmcnt(0)
	v_mfma_f32_16x16x32_bf16 v[126:129], v[130:133], v[162:165], v[126:129]
	v_mfma_f32_16x16x32_bf16 v[122:125], v[138:141], v[162:165], v[122:125]
	v_mfma_f32_16x16x32_bf16 v[118:121], v[130:133], v[170:173], v[118:121]
	v_mfma_f32_16x16x32_bf16 v[102:105], v[138:141], v[170:173], v[102:105]
	v_mfma_f32_16x16x32_bf16 v[94:97], v[130:133], v[178:181], v[94:97]
	v_mfma_f32_16x16x32_bf16 v[90:93], v[138:141], v[178:181], v[90:93]
	v_mfma_f32_16x16x32_bf16 v[78:81], v[130:133], v[198:201], v[78:81]
	v_mfma_f32_16x16x32_bf16 v[74:77], v[138:141], v[198:201], v[74:77]
	v_mfma_f32_16x16x32_bf16 v[126:129], v[134:137], v[166:169], v[126:129]
	v_mfma_f32_16x16x32_bf16 v[122:125], v[142:145], v[166:169], v[122:125]
	v_mfma_f32_16x16x32_bf16 v[118:121], v[134:137], v[174:177], v[118:121]
	v_mfma_f32_16x16x32_bf16 v[102:105], v[142:145], v[174:177], v[102:105]
	v_mfma_f32_16x16x32_bf16 v[94:97], v[134:137], v[182:185], v[94:97]
	v_mfma_f32_16x16x32_bf16 v[90:93], v[142:145], v[182:185], v[90:93]
	v_mfma_f32_16x16x32_bf16 v[78:81], v[134:137], v[202:205], v[78:81]
	v_mfma_f32_16x16x32_bf16 v[74:77], v[142:145], v[202:205], v[74:77]
	s_setprio 0
	s_setprio 1
	v_mfma_f32_16x16x32_bf16 v[114:117], v[146:149], v[162:165], v[114:117]
	v_mfma_f32_16x16x32_bf16 v[110:113], v[154:157], v[162:165], v[110:113]
	v_mfma_f32_16x16x32_bf16 v[106:109], v[146:149], v[170:173], v[106:109]
	v_mfma_f32_16x16x32_bf16 v[98:101], v[154:157], v[170:173], v[98:101]
	v_mfma_f32_16x16x32_bf16 v[86:89], v[146:149], v[178:181], v[86:89]
	v_mfma_f32_16x16x32_bf16 v[82:85], v[154:157], v[178:181], v[82:85]
	v_mfma_f32_16x16x32_bf16 v[70:73], v[146:149], v[198:201], v[70:73]
	v_mfma_f32_16x16x32_bf16 v[66:69], v[154:157], v[198:201], v[66:69]
	v_mfma_f32_16x16x32_bf16 v[114:117], v[150:153], v[166:169], v[114:117]
	v_mfma_f32_16x16x32_bf16 v[110:113], v[158:161], v[166:169], v[110:113]
	v_mfma_f32_16x16x32_bf16 v[106:109], v[150:153], v[174:177], v[106:109]
	v_mfma_f32_16x16x32_bf16 v[98:101], v[158:161], v[174:177], v[98:101]
	v_mfma_f32_16x16x32_bf16 v[86:89], v[150:153], v[182:185], v[86:89]
	v_mfma_f32_16x16x32_bf16 v[82:85], v[158:161], v[182:185], v[82:85]
	v_mfma_f32_16x16x32_bf16 v[70:73], v[150:153], v[202:205], v[70:73]
	v_mfma_f32_16x16x32_bf16 v[66:69], v[158:161], v[202:205], v[66:69]
	s_setprio 0
	s_barrier
	s_add_i32 s47, s47, s57
	v_lshl_add_u64 v[206:207], s[66:67], 0, v[188:189]
	s_mov_b32 m0, s47
	ds_read_b128 v[162:165], v238 offset:16384
	ds_read_b128 v[166:169], v238 offset:17408
	ds_read_b128 v[170:173], v238 offset:18432
	ds_read_b128 v[174:177], v238 offset:19456
	ds_read_b128 v[178:181], v238 offset:20480
	ds_read_b128 v[182:185], v238 offset:21504
	ds_read_b128 v[198:201], v238 offset:22528
	ds_read_b128 v[202:205], v238 offset:23552
	global_load_lds_dwordx4 v[206:207], off
	s_add_i32 m0, s47, 0x2000
	v_lshl_add_u64 v[208:209], s[66:67], 0, v[192:193]
	s_add_u32 s66, s66, s69
	s_addc_u32 s67, s67, 0
	s_add_i32 s1, s1, s57
	global_load_lds_dwordx4 v[208:209], off
	v_lshl_add_u64 v[210:211], s[66:67], 0, v[188:189]
	s_mov_b32 m0, s1
	v_lshl_add_u64 v[212:213], s[66:67], 0, v[192:193]
	global_load_lds_dwordx4 v[210:211], off
	s_add_i32 m0, s1, 0x2000
	v_lshl_add_u64 v[214:215], s[34:35], 0, v[186:187]
	global_load_lds_dwordx4 v[212:213], off
	s_mov_b32 m0, s90
	v_lshl_add_u64 v[216:217], s[34:35], 0, v[190:191]
	global_load_lds_dwordx4 v[214:215], off
	s_mov_b32 m0, s60
	s_nop 0
	global_load_lds_dwordx4 v[216:217], off
	s_waitcnt vmcnt(8)
	s_waitcnt lgkmcnt(0)
	s_barrier
	s_setprio 1
	s_waitcnt lgkmcnt(0)
	s_cmp_lg_u32 s101, 0
	s_cbranch_scc1 .Lhu_skip0
	v_mfma_f32_16x16x32_bf16 v[62:65], v[130:133], v[162:165], v[62:65]
	v_mfma_f32_16x16x32_bf16 v[58:61], v[138:141], v[162:165], v[58:61]
	v_mfma_f32_16x16x32_bf16 v[46:49], v[130:133], v[170:173], v[46:49]
	v_mfma_f32_16x16x32_bf16 v[42:45], v[138:141], v[170:173], v[42:45]
	v_mfma_f32_16x16x32_bf16 v[30:33], v[130:133], v[178:181], v[30:33]
	v_mfma_f32_16x16x32_bf16 v[26:29], v[138:141], v[178:181], v[26:29]
	v_mfma_f32_16x16x32_bf16 v[14:17], v[130:133], v[198:201], v[14:17]
	v_mfma_f32_16x16x32_bf16 v[10:13], v[138:141], v[198:201], v[10:13]
	v_mfma_f32_16x16x32_bf16 v[62:65], v[134:137], v[166:169], v[62:65]
	v_mfma_f32_16x16x32_bf16 v[58:61], v[142:145], v[166:169], v[58:61]
	v_mfma_f32_16x16x32_bf16 v[46:49], v[134:137], v[174:177], v[46:49]
	v_mfma_f32_16x16x32_bf16 v[42:45], v[142:145], v[174:177], v[42:45]
	v_mfma_f32_16x16x32_bf16 v[30:33], v[134:137], v[182:185], v[30:33]
	v_mfma_f32_16x16x32_bf16 v[26:29], v[142:145], v[182:185], v[26:29]
	v_mfma_f32_16x16x32_bf16 v[14:17], v[134:137], v[202:205], v[14:17]
	v_mfma_f32_16x16x32_bf16 v[10:13], v[142:145], v[202:205], v[10:13]
	s_setprio 0
	s_setprio 1
	v_mfma_f32_16x16x32_bf16 v[54:57], v[146:149], v[162:165], v[54:57]
	v_mfma_f32_16x16x32_bf16 v[50:53], v[154:157], v[162:165], v[50:53]
	v_mfma_f32_16x16x32_bf16 v[38:41], v[146:149], v[170:173], v[38:41]
	v_mfma_f32_16x16x32_bf16 v[34:37], v[154:157], v[170:173], v[34:37]
	v_mfma_f32_16x16x32_bf16 v[22:25], v[146:149], v[178:181], v[22:25]
	v_mfma_f32_16x16x32_bf16 v[18:21], v[154:157], v[178:181], v[18:21]
	v_mfma_f32_16x16x32_bf16 v[6:9], v[146:149], v[198:201], v[6:9]
	v_mfma_f32_16x16x32_bf16 v[2:5], v[154:157], v[198:201], v[2:5]
	v_mfma_f32_16x16x32_bf16 v[54:57], v[150:153], v[166:169], v[54:57]
	v_mfma_f32_16x16x32_bf16 v[50:53], v[158:161], v[166:169], v[50:53]
	v_mfma_f32_16x16x32_bf16 v[38:41], v[150:153], v[174:177], v[38:41]
	v_mfma_f32_16x16x32_bf16 v[34:37], v[158:161], v[174:177], v[34:37]
	v_mfma_f32_16x16x32_bf16 v[22:25], v[150:153], v[182:185], v[22:25]
	v_mfma_f32_16x16x32_bf16 v[18:21], v[158:161], v[182:185], v[18:21]
	v_mfma_f32_16x16x32_bf16 v[6:9], v[150:153], v[202:205], v[6:9]
	v_mfma_f32_16x16x32_bf16 v[2:5], v[158:161], v[202:205], v[2:5]
.Lhu_skip0:
	s_setprio 0
	s_barrier
	s_add_i32 s1, 0, 0x18000
	s_add_i32 s47, 0, 0x1c000
	v_add_u32_e32 v142, s1, v234
	v_add_u32_e32 v158, s47, v234
	ds_read_b128 v[130:133], v142
	ds_read_b128 v[134:137], v142 offset:1024
	ds_read_b128 v[138:141], v142 offset:2048
	ds_read_b128 v[142:145], v142 offset:3072
	ds_read_b128 v[146:149], v158
	ds_read_b128 v[150:153], v158 offset:1024
	ds_read_b128 v[154:157], v158 offset:2048
	ds_read_b128 v[158:161], v158 offset:3072
	s_add_u32 s34, s34, s16
	s_addc_u32 s35, s35, 0
	s_mov_b32 m0, s61
	v_lshl_add_u64 v[218:219], s[34:35], 0, v[186:187]
	ds_read_b128 v[162:165], v238 offset:32768
	ds_read_b128 v[166:169], v238 offset:33792
	ds_read_b128 v[170:173], v238 offset:34816
	ds_read_b128 v[174:177], v238 offset:35840
	ds_read_b128 v[178:181], v238 offset:36864
	ds_read_b128 v[182:185], v238 offset:37888
	ds_read_b128 v[198:201], v238 offset:38912
	ds_read_b128 v[202:205], v238 offset:39936
	global_load_lds_dwordx4 v[218:219], off
	v_lshl_add_u64 v[218:219], s[34:35], 0, v[190:191]
	s_mov_b32 m0, s71
	s_nop 0
	global_load_lds_dwordx4 v[218:219], off
	s_waitcnt vmcnt(8)
	s_waitcnt lgkmcnt(0)
	s_barrier
	s_setprio 1
	s_waitcnt lgkmcnt(0)
	v_mfma_f32_16x16x32_bf16 v[126:129], v[130:133], v[162:165], v[126:129]
	v_mfma_f32_16x16x32_bf16 v[122:125], v[138:141], v[162:165], v[122:125]
	v_mfma_f32_16x16x32_bf16 v[118:121], v[130:133], v[170:173], v[118:121]
	v_mfma_f32_16x16x32_bf16 v[102:105], v[138:141], v[170:173], v[102:105]
	v_mfma_f32_16x16x32_bf16 v[94:97], v[130:133], v[178:181], v[94:97]
	v_mfma_f32_16x16x32_bf16 v[90:93], v[138:141], v[178:181], v[90:93]
	v_mfma_f32_16x16x32_bf16 v[78:81], v[130:133], v[198:201], v[78:81]
	v_mfma_f32_16x16x32_bf16 v[74:77], v[138:141], v[198:201], v[74:77]
	v_mfma_f32_16x16x32_bf16 v[126:129], v[134:137], v[166:169], v[126:129]
	v_mfma_f32_16x16x32_bf16 v[122:125], v[142:145], v[166:169], v[122:125]
	v_mfma_f32_16x16x32_bf16 v[118:121], v[134:137], v[174:177], v[118:121]
	v_mfma_f32_16x16x32_bf16 v[102:105], v[142:145], v[174:177], v[102:105]
	v_mfma_f32_16x16x32_bf16 v[94:97], v[134:137], v[182:185], v[94:97]
	v_mfma_f32_16x16x32_bf16 v[90:93], v[142:145], v[182:185], v[90:93]
	v_mfma_f32_16x16x32_bf16 v[78:81], v[134:137], v[202:205], v[78:81]
	v_mfma_f32_16x16x32_bf16 v[74:77], v[142:145], v[202:205], v[74:77]
	s_setprio 0
	s_setprio 1
	v_mfma_f32_16x16x32_bf16 v[114:117], v[146:149], v[162:165], v[114:117]
	v_mfma_f32_16x16x32_bf16 v[110:113], v[154:157], v[162:165], v[110:113]
	v_mfma_f32_16x16x32_bf16 v[106:109], v[146:149], v[170:173], v[106:109]
	v_mfma_f32_16x16x32_bf16 v[98:101], v[154:157], v[170:173], v[98:101]
	v_mfma_f32_16x16x32_bf16 v[86:89], v[146:149], v[178:181], v[86:89]
	v_mfma_f32_16x16x32_bf16 v[82:85], v[154:157], v[178:181], v[82:85]
	v_mfma_f32_16x16x32_bf16 v[70:73], v[146:149], v[198:201], v[70:73]
	v_mfma_f32_16x16x32_bf16 v[66:69], v[154:157], v[198:201], v[66:69]
	v_mfma_f32_16x16x32_bf16 v[114:117], v[150:153], v[166:169], v[114:117]
	v_mfma_f32_16x16x32_bf16 v[110:113], v[158:161], v[166:169], v[110:113]
	v_mfma_f32_16x16x32_bf16 v[106:109], v[150:153], v[174:177], v[106:109]
	v_mfma_f32_16x16x32_bf16 v[98:101], v[158:161], v[174:177], v[98:101]
	v_mfma_f32_16x16x32_bf16 v[86:89], v[150:153], v[182:185], v[86:89]
	v_mfma_f32_16x16x32_bf16 v[82:85], v[158:161], v[182:185], v[82:85]
	v_mfma_f32_16x16x32_bf16 v[70:73], v[150:153], v[202:205], v[70:73]
	v_mfma_f32_16x16x32_bf16 v[66:69], v[158:161], v[202:205], v[66:69]
	s_setprio 0
	s_barrier
	s_add_i32 s1, s1, s57
	v_lshl_add_u64 v[206:207], v[206:207], 0, s[36:37]
	s_mov_b32 m0, s1
	ds_read_b128 v[162:165], v238 offset:49152
	ds_read_b128 v[166:169], v238 offset:50176
	ds_read_b128 v[170:173], v238 offset:51200
	ds_read_b128 v[174:177], v238 offset:52224
	ds_read_b128 v[178:181], v238 offset:53248
	ds_read_b128 v[182:185], v238 offset:54272
	ds_read_b128 v[198:201], v238 offset:55296
	ds_read_b128 v[202:205], v238 offset:56320
	global_load_lds_dwordx4 v[206:207], off
	v_lshl_add_u64 v[206:207], v[208:209], 0, s[36:37]
	s_add_i32 m0, s1, 0x2000
	s_add_i32 s1, s47, s57
	global_load_lds_dwordx4 v[206:207], off
	v_lshl_add_u64 v[206:207], v[210:211], 0, s[36:37]
	s_mov_b32 m0, s1
	s_nop 0
	global_load_lds_dwordx4 v[206:207], off
	v_lshl_add_u64 v[206:207], v[212:213], 0, s[36:37]
	s_add_i32 m0, s1, 0x2000
	s_nop 0
	global_load_lds_dwordx4 v[206:207], off
	v_lshl_add_u64 v[206:207], v[214:215], 0, s[36:37]
	s_mov_b32 m0, s64
	s_nop 0
	global_load_lds_dwordx4 v[206:207], off
	v_lshl_add_u64 v[206:207], v[216:217], 0, s[36:37]
	s_mov_b32 m0, s65
	s_nop 0
	global_load_lds_dwordx4 v[206:207], off
	s_waitcnt vmcnt(8)
	s_waitcnt lgkmcnt(0)
	s_barrier
	s_setprio 1
	s_waitcnt lgkmcnt(0)
	s_cmp_lg_u32 s101, 0
	s_cbranch_scc1 .Lhu_skip1
	v_mfma_f32_16x16x32_bf16 v[62:65], v[130:133], v[162:165], v[62:65]
	v_mfma_f32_16x16x32_bf16 v[58:61], v[138:141], v[162:165], v[58:61]
	v_mfma_f32_16x16x32_bf16 v[46:49], v[130:133], v[170:173], v[46:49]
	v_mfma_f32_16x16x32_bf16 v[42:45], v[138:141], v[170:173], v[42:45]
	v_mfma_f32_16x16x32_bf16 v[30:33], v[130:133], v[178:181], v[30:33]
	v_mfma_f32_16x16x32_bf16 v[26:29], v[138:141], v[178:181], v[26:29]
	v_mfma_f32_16x16x32_bf16 v[14:17], v[130:133], v[198:201], v[14:17]
	v_mfma_f32_16x16x32_bf16 v[10:13], v[138:141], v[198:201], v[10:13]
	v_mfma_f32_16x16x32_bf16 v[62:65], v[134:137], v[166:169], v[62:65]
	v_mfma_f32_16x16x32_bf16 v[58:61], v[142:145], v[166:169], v[58:61]
	v_mfma_f32_16x16x32_bf16 v[46:49], v[134:137], v[174:177], v[46:49]
	v_mfma_f32_16x16x32_bf16 v[42:45], v[142:145], v[174:177], v[42:45]
	v_mfma_f32_16x16x32_bf16 v[30:33], v[134:137], v[182:185], v[30:33]
	v_mfma_f32_16x16x32_bf16 v[26:29], v[142:145], v[182:185], v[26:29]
	v_mfma_f32_16x16x32_bf16 v[14:17], v[134:137], v[202:205], v[14:17]
	v_mfma_f32_16x16x32_bf16 v[10:13], v[142:145], v[202:205], v[10:13]
	s_setprio 0
	s_setprio 1
	v_mfma_f32_16x16x32_bf16 v[54:57], v[146:149], v[162:165], v[54:57]
	v_mfma_f32_16x16x32_bf16 v[50:53], v[154:157], v[162:165], v[50:53]
	v_mfma_f32_16x16x32_bf16 v[38:41], v[146:149], v[170:173], v[38:41]
	v_mfma_f32_16x16x32_bf16 v[34:37], v[154:157], v[170:173], v[34:37]
	v_mfma_f32_16x16x32_bf16 v[22:25], v[146:149], v[178:181], v[22:25]
	v_mfma_f32_16x16x32_bf16 v[18:21], v[154:157], v[178:181], v[18:21]
	v_mfma_f32_16x16x32_bf16 v[6:9], v[146:149], v[198:201], v[6:9]
	v_mfma_f32_16x16x32_bf16 v[2:5], v[154:157], v[198:201], v[2:5]
	v_mfma_f32_16x16x32_bf16 v[54:57], v[150:153], v[166:169], v[54:57]
	v_mfma_f32_16x16x32_bf16 v[50:53], v[158:161], v[166:169], v[50:53]
	v_mfma_f32_16x16x32_bf16 v[38:41], v[150:153], v[174:177], v[38:41]
	v_mfma_f32_16x16x32_bf16 v[34:37], v[158:161], v[174:177], v[34:37]
	v_mfma_f32_16x16x32_bf16 v[22:25], v[150:153], v[182:185], v[22:25]
	v_mfma_f32_16x16x32_bf16 v[18:21], v[158:161], v[182:185], v[18:21]
	v_mfma_f32_16x16x32_bf16 v[6:9], v[150:153], v[202:205], v[6:9]
	v_mfma_f32_16x16x32_bf16 v[2:5], v[158:161], v[202:205], v[2:5]
.Lhu_skip1:
	s_setprio 0
	s_barrier
	s_add_u32 s80, s80, 0x100
	s_addc_u32 s81, s81, 0
	s_add_u32 vcc_lo, vcc_lo, 0x100
	s_addc_u32 vcc_hi, vcc_hi, 0
	s_cmp_ge_u32 s0, s91
	s_mov_b32 s34, s0
	s_cbranch_scc0 .LBB0_169
	v_readlane_b32 s0, v243, 28
	v_readlane_b32 s1, v243, 29
	s_and_b64 vcc, exec, s[0:1]
	s_cbranch_vccz .LBB0_174
	s_barrier
	v_lshl_add_u32 v198, s99, 8, v1
	s_cmp_eq_u32 s101, 2
	s_cselect_b32 s0, 0x80, 0
	v_add_u32_e32 v198, s0, v198
	s_cmp_lt_i32 s70, 1
	s_mov_b64 s[34:35], -1
	s_cbranch_scc0 .LBB0_175

.LBB0_173:
	v_ashrrev_i32_e32 v199, 31, v198
	v_lshl_add_u64 v[132:133], v[198:199], 2, s[50:51]
	global_load_dword v136, v[132:133], off
	global_load_dword v137, v[132:133], off offset:64
	v_lshl_or_b32 v130, s88, 7, v237
	s_waitcnt lgkmcnt(0)
	v_mad_u64_u32 v[134:135], s[0:1], v198, s29, v[130:131]
	global_load_dword v135, v[132:133], off offset:128
	global_load_dword v138, v[132:133], off offset:192
	global_load_dword v139, v[132:133], off offset:512
	global_load_dword v140, v[132:133], off offset:576
	global_load_dword v131, v[132:133], off offset:640
	global_load_dword v130, v[132:133], off offset:704
	v_lshlrev_b32_e32 v133, 1, v134
	s_mul_i32 s0, s29, 0x50
	s_waitcnt vmcnt(0)
	v_fmamk_f32 v132, v136, 0x3a800000, v221
	v_rsq_f32_e32 v132, v132
	v_fmamk_f32 v136, v137, 0x3a800000, v221
	v_rsq_f32_e32 v136, v136
	v_pk_mul_f32 v[126:127], v[126:127], v[132:133] op_sel_hi:[1,0]
	v_pk_mul_f32 v[114:115], v[114:115], v[132:133] op_sel_hi:[1,0]
	v_pk_mul_f32 v[128:129], v[128:129], v[132:133] op_sel_hi:[1,0]
	v_pk_mul_f32 v[116:117], v[116:117], v[132:133] op_sel_hi:[1,0]
	v_pk_mul_f32 v[122:123], v[122:123], v[132:133] op_sel_hi:[1,0]
	v_pk_mul_f32 v[110:111], v[110:111], v[132:133] op_sel_hi:[1,0]
	v_pk_mul_f32 v[124:125], v[124:125], v[132:133] op_sel_hi:[1,0]
	v_pk_mul_f32 v[112:113], v[112:113], v[132:133] op_sel_hi:[1,0]
	v_pk_mul_f32 v[118:119], v[118:119], v[136:137] op_sel_hi:[1,0]
	v_pk_mul_f32 v[106:107], v[106:107], v[136:137] op_sel_hi:[1,0]
	v_pk_mul_f32 v[120:121], v[120:121], v[136:137] op_sel_hi:[1,0]
	v_pk_mul_f32 v[108:109], v[108:109], v[136:137] op_sel_hi:[1,0]
	v_pk_mul_f32 v[102:103], v[102:103], v[136:137] op_sel_hi:[1,0]
	v_mul_f32_e32 v132, 0xbfb8aa3b, v126
	v_pk_mul_f32 v[114:115], v[126:127], v[114:115]
	v_mul_f32_e32 v126, 0xbfb8aa3b, v127
	v_mul_f32_e32 v127, 0xbfb8aa3b, v128
	v_pk_mul_f32 v[116:117], v[128:129], v[116:117]
	v_mul_f32_e32 v128, 0xbfb8aa3b, v129
	v_mul_f32_e32 v129, 0xbfb8aa3b, v122
	v_pk_mul_f32 v[110:111], v[122:123], v[110:111]
	v_mul_f32_e32 v122, 0xbfb8aa3b, v123
	v_mul_f32_e32 v123, 0xbfb8aa3b, v124
	v_pk_mul_f32 v[112:113], v[124:125], v[112:113]
	v_mul_f32_e32 v124, 0xbfb8aa3b, v125
	v_mul_f32_e32 v125, 0xbfb8aa3b, v118
	v_pk_mul_f32 v[106:107], v[118:119], v[106:107]
	v_mul_f32_e32 v118, 0xbfb8aa3b, v119
	v_mul_f32_e32 v119, 0xbfb8aa3b, v120
	v_pk_mul_f32 v[108:109], v[120:121], v[108:109]
	v_mul_f32_e32 v120, 0xbfb8aa3b, v121
	v_mul_f32_e32 v121, 0xbfb8aa3b, v102
	v_exp_f32_e32 v132, v132
	v_exp_f32_e32 v126, v126
	v_exp_f32_e32 v127, v127
	v_exp_f32_e32 v128, v128
	v_exp_f32_e32 v129, v129
	v_exp_f32_e32 v122, v122
	v_exp_f32_e32 v123, v123
	v_exp_f32_e32 v124, v124
	v_mul_f32_e32 v137, 0xbfb8aa3b, v103
	v_exp_f32_e32 v125, v125
	v_exp_f32_e32 v118, v118
	v_exp_f32_e32 v119, v119
	v_exp_f32_e32 v120, v120
	v_exp_f32_e32 v121, v121
	v_exp_f32_e32 v137, v137
	v_add_f32_e32 v132, 1.0, v132
	v_add_f32_e32 v126, 1.0, v126
	v_add_f32_e32 v127, 1.0, v127
	v_add_f32_e32 v128, 1.0, v128
	v_add_f32_e32 v129, 1.0, v129
	v_add_f32_e32 v141, 1.0, v122
	v_add_f32_e32 v142, 1.0, v123
	v_add_f32_e32 v143, 1.0, v124
	v_add_f32_e32 v144, 1.0, v125
	v_add_f32_e32 v145, 1.0, v118
	v_add_f32_e32 v146, 1.0, v119
	v_add_f32_e32 v147, 1.0, v120
	v_add_f32_e32 v148, 1.0, v121
	v_rcp_f32_e32 v118, v132
	v_rcp_f32_e32 v119, v126
	v_rcp_f32_e32 v120, v127
	v_rcp_f32_e32 v121, v128
	v_rcp_f32_e32 v122, v129
	v_rcp_f32_e32 v123, v141
	v_rcp_f32_e32 v124, v142
	v_rcp_f32_e32 v125, v143
	v_rcp_f32_e32 v126, v144
	v_rcp_f32_e32 v127, v145
	v_rcp_f32_e32 v128, v146
	v_rcp_f32_e32 v129, v147
	v_pk_mul_f32 v[98:99], v[98:99], v[136:137] op_sel_hi:[1,0]
	v_pk_mul_f32 v[114:115], v[114:115], v[118:119]
	v_pk_mul_f32 v[98:99], v[102:103], v[98:99]
	v_pk_mul_f32 v[102:103], v[104:105], v[136:137] op_sel_hi:[1,0]
	v_pk_mul_f32 v[116:117], v[116:117], v[120:121]
	v_mul_f32_e32 v104, 0xbfb8aa3b, v102
	v_mul_f32_e32 v105, 0xbfb8aa3b, v103
	v_pk_mul_f32 v[110:111], v[110:111], v[122:123]
	v_pk_mul_f32 v[112:113], v[112:113], v[124:125]
	v_exp_f32_e32 v104, v104
	v_exp_f32_e32 v105, v105
	v_pk_mul_f32 v[118:119], v[106:107], v[126:127]
	v_pk_mul_f32 v[120:121], v[108:109], v[128:129]
	v_cvt_pk_bf16_f32 v106, v114, v115
	v_cvt_pk_bf16_f32 v107, v116, v117
	v_cvt_pk_bf16_f32 v108, v110, v111
	v_cvt_pk_bf16_f32 v109, v112, v113
	buffer_store_dwordx4 v[106:109], v133, s[20:23], 0 offen sc1
	v_add_f32_e32 v104, 1.0, v104
	v_add_f32_e32 v105, 1.0, v105
	v_add_f32_e32 v107, 1.0, v137
	v_rcp_f32_e32 v106, v148
	v_rcp_f32_e32 v107, v107
	v_rcp_f32_e32 v104, v104
	v_rcp_f32_e32 v105, v105
	v_pk_mul_f32 v[106:107], v[98:99], v[106:107]
	v_pk_mul_f32 v[98:99], v[100:101], v[136:137] op_sel_hi:[1,0]
	s_nop 0
	v_pk_mul_f32 v[98:99], v[102:103], v[98:99]
	s_nop 0
	v_pk_mul_f32 v[102:103], v[98:99], v[104:105]
	v_fmamk_f32 v98, v135, 0x3a800000, v221
	v_rsq_f32_e32 v104, v98
	v_add_u32_e32 v105, s53, v134
	v_lshlrev_b32_e32 v108, 1, v105
	v_cvt_pk_bf16_f32 v98, v118, v119
	v_pk_mul_f32 v[94:95], v[94:95], v[104:105] op_sel_hi:[1,0]
	v_cvt_pk_bf16_f32 v99, v120, v121
	v_mul_f32_e32 v100, 0xbfb8aa3b, v94
	v_exp_f32_e32 v109, v100
	v_cvt_pk_bf16_f32 v100, v106, v107
	v_cvt_pk_bf16_f32 v101, v102, v103
	buffer_store_dwordx4 v[98:101], v108, s[20:23], 0 offen sc1
	v_pk_mul_f32 v[86:87], v[86:87], v[104:105] op_sel_hi:[1,0]
	v_pk_mul_f32 v[90:91], v[90:91], v[104:105] op_sel_hi:[1,0]
	v_mul_f32_e32 v99, 0xbfb8aa3b, v95
	v_exp_f32_e32 v99, v99
	v_add_f32_e32 v98, 1.0, v109
	v_pk_mul_f32 v[86:87], v[94:95], v[86:87]
	v_rcp_f32_e32 v98, v98
	v_add_f32_e32 v94, 1.0, v99
	v_rcp_f32_e32 v99, v94
	v_pk_mul_f32 v[94:95], v[96:97], v[104:105] op_sel_hi:[1,0]
	v_pk_mul_f32 v[88:89], v[88:89], v[104:105] op_sel_hi:[1,0]
	v_mul_f32_e32 v97, 0xbfb8aa3b, v95
	v_pk_mul_f32 v[86:87], v[86:87], v[98:99]
	v_mul_f32_e32 v98, 0xbfb8aa3b, v90
	v_pk_mul_f32 v[88:89], v[94:95], v[88:89]
	v_mul_f32_e32 v95, 0xbfb8aa3b, v91
	v_pk_mul_f32 v[82:83], v[82:83], v[104:105] op_sel_hi:[1,0]
	v_exp_f32_e32 v98, v98
	v_exp_f32_e32 v95, v95
	v_pk_mul_f32 v[82:83], v[90:91], v[82:83]
	v_pk_mul_f32 v[90:91], v[92:93], v[104:105] op_sel_hi:[1,0]
	v_mul_f32_e32 v96, 0xbfb8aa3b, v94
	v_mul_f32_e32 v92, 0xbfb8aa3b, v90
	v_mul_f32_e32 v93, 0xbfb8aa3b, v91
	v_exp_f32_e32 v92, v92
	v_exp_f32_e32 v93, v93
	v_add_f32_e32 v94, 1.0, v98
	v_add_f32_e32 v95, 1.0, v95
	v_rcp_f32_e32 v94, v94
	v_rcp_f32_e32 v95, v95
	v_add_f32_e32 v92, 1.0, v92
	v_add_f32_e32 v93, 1.0, v93
	v_rcp_f32_e32 v92, v92
	v_rcp_f32_e32 v93, v93
	v_exp_f32_e32 v96, v96
	v_exp_f32_e32 v97, v97
	v_pk_mul_f32 v[94:95], v[82:83], v[94:95]
	v_pk_mul_f32 v[82:83], v[84:85], v[104:105] op_sel_hi:[1,0]
	v_add_f32_e32 v96, 1.0, v96
	v_pk_mul_f32 v[82:83], v[90:91], v[82:83]
	v_add_f32_e32 v97, 1.0, v97
	v_pk_mul_f32 v[90:91], v[82:83], v[92:93]
	v_fmamk_f32 v82, v138, 0x3a800000, v221
	v_rsq_f32_e32 v92, v82
	v_rcp_f32_e32 v96, v96
	v_rcp_f32_e32 v97, v97
	v_add_u32_e32 v93, s53, v105
	v_pk_mul_f32 v[78:79], v[78:79], v[92:93] op_sel_hi:[1,0]
	v_cvt_pk_bf16_f32 v82, v86, v87
	v_pk_mul_f32 v[88:89], v[88:89], v[96:97]
	v_mul_f32_e32 v84, 0xbfb8aa3b, v78
	v_lshlrev_b32_e32 v96, 1, v93
	v_cvt_pk_bf16_f32 v83, v88, v89
	v_exp_f32_e32 v86, v84
	v_cvt_pk_bf16_f32 v84, v94, v95
	v_cvt_pk_bf16_f32 v85, v90, v91
	buffer_store_dwordx4 v[82:85], v96, s[20:23], 0 offen sc1
	v_pk_mul_f32 v[70:71], v[70:71], v[92:93] op_sel_hi:[1,0]
	v_pk_mul_f32 v[74:75], v[74:75], v[92:93] op_sel_hi:[1,0]
	v_mul_f32_e32 v83, 0xbfb8aa3b, v79
	v_exp_f32_e32 v83, v83
	v_add_f32_e32 v82, 1.0, v86
	v_pk_mul_f32 v[70:71], v[78:79], v[70:71]
	v_rcp_f32_e32 v82, v82
	v_add_f32_e32 v78, 1.0, v83
	v_rcp_f32_e32 v83, v78
	v_pk_mul_f32 v[78:79], v[80:81], v[92:93] op_sel_hi:[1,0]
	v_pk_mul_f32 v[72:73], v[72:73], v[92:93] op_sel_hi:[1,0]
	v_mul_f32_e32 v81, 0xbfb8aa3b, v79
	v_pk_mul_f32 v[70:71], v[70:71], v[82:83]
	v_mul_f32_e32 v82, 0xbfb8aa3b, v74
	v_pk_mul_f32 v[72:73], v[78:79], v[72:73]
	v_mul_f32_e32 v79, 0xbfb8aa3b, v75
	v_pk_mul_f32 v[66:67], v[66:67], v[92:93] op_sel_hi:[1,0]
	v_exp_f32_e32 v82, v82
	v_exp_f32_e32 v79, v79
	v_pk_mul_f32 v[66:67], v[74:75], v[66:67]
	v_pk_mul_f32 v[74:75], v[76:77], v[92:93] op_sel_hi:[1,0]
	v_mul_f32_e32 v80, 0xbfb8aa3b, v78
	v_mul_f32_e32 v76, 0xbfb8aa3b, v74
	v_mul_f32_e32 v77, 0xbfb8aa3b, v75
	v_exp_f32_e32 v76, v76
	v_exp_f32_e32 v77, v77
	v_add_f32_e32 v78, 1.0, v82
	v_add_f32_e32 v79, 1.0, v79
	v_rcp_f32_e32 v78, v78
	v_rcp_f32_e32 v79, v79
	v_add_f32_e32 v76, 1.0, v76
	v_add_f32_e32 v77, 1.0, v77
	v_rcp_f32_e32 v76, v76
	v_rcp_f32_e32 v77, v77
	v_exp_f32_e32 v80, v80
	v_exp_f32_e32 v81, v81
	v_pk_mul_f32 v[78:79], v[66:67], v[78:79]
	v_pk_mul_f32 v[66:67], v[68:69], v[92:93] op_sel_hi:[1,0]
	v_add_f32_e32 v80, 1.0, v80
	v_pk_mul_f32 v[66:67], v[74:75], v[66:67]
	v_add_f32_e32 v81, 1.0, v81
	v_pk_mul_f32 v[74:75], v[66:67], v[76:77]
	v_fmamk_f32 v66, v139, 0x3a800000, v221
	v_rsq_f32_e32 v76, v66
	v_rcp_f32_e32 v80, v80
	v_rcp_f32_e32 v81, v81
	v_add_u32_e32 v77, s53, v93
	v_pk_mul_f32 v[62:63], v[62:63], v[76:77] op_sel_hi:[1,0]
	v_cvt_pk_bf16_f32 v66, v70, v71
	v_pk_mul_f32 v[72:73], v[72:73], v[80:81]
	v_mul_f32_e32 v68, 0xbfb8aa3b, v62
	v_lshlrev_b32_e32 v80, 1, v77
	v_cvt_pk_bf16_f32 v67, v72, v73
	v_exp_f32_e32 v70, v68
	v_cvt_pk_bf16_f32 v68, v78, v79
	v_cvt_pk_bf16_f32 v69, v74, v75
	buffer_store_dwordx4 v[66:69], v80, s[20:23], 0 offen sc1
	s_cmp_lg_u32 s101, 0
	s_cbranch_scc1 .Lhu_epi_tail
	v_pk_mul_f32 v[54:55], v[54:55], v[76:77] op_sel_hi:[1,0]
	v_pk_mul_f32 v[58:59], v[58:59], v[76:77] op_sel_hi:[1,0]
	v_mul_f32_e32 v67, 0xbfb8aa3b, v63
	v_exp_f32_e32 v67, v67
	v_add_f32_e32 v66, 1.0, v70
	v_pk_mul_f32 v[54:55], v[62:63], v[54:55]
	v_rcp_f32_e32 v66, v66
	v_add_f32_e32 v62, 1.0, v67
	v_rcp_f32_e32 v67, v62
	v_pk_mul_f32 v[62:63], v[64:65], v[76:77] op_sel_hi:[1,0]
	v_pk_mul_f32 v[56:57], v[56:57], v[76:77] op_sel_hi:[1,0]
	v_mul_f32_e32 v65, 0xbfb8aa3b, v63
	v_pk_mul_f32 v[54:55], v[54:55], v[66:67]
	v_mul_f32_e32 v66, 0xbfb8aa3b, v58
	v_pk_mul_f32 v[56:57], v[62:63], v[56:57]
	v_mul_f32_e32 v63, 0xbfb8aa3b, v59
	v_pk_mul_f32 v[50:51], v[50:51], v[76:77] op_sel_hi:[1,0]
	v_exp_f32_e32 v66, v66
	v_exp_f32_e32 v63, v63
	v_pk_mul_f32 v[50:51], v[58:59], v[50:51]
	v_pk_mul_f32 v[58:59], v[60:61], v[76:77] op_sel_hi:[1,0]
	v_mul_f32_e32 v64, 0xbfb8aa3b, v62
	v_mul_f32_e32 v60, 0xbfb8aa3b, v58
	v_mul_f32_e32 v61, 0xbfb8aa3b, v59
	v_exp_f32_e32 v60, v60
	v_exp_f32_e32 v61, v61
	v_add_f32_e32 v62, 1.0, v66
	v_add_f32_e32 v63, 1.0, v63
	v_rcp_f32_e32 v62, v62
	v_rcp_f32_e32 v63, v63
	v_add_f32_e32 v60, 1.0, v60
	v_add_f32_e32 v61, 1.0, v61
	v_rcp_f32_e32 v60, v60
	v_rcp_f32_e32 v61, v61
	v_exp_f32_e32 v64, v64
	v_exp_f32_e32 v65, v65
	v_pk_mul_f32 v[62:63], v[50:51], v[62:63]
	v_pk_mul_f32 v[50:51], v[52:53], v[76:77] op_sel_hi:[1,0]
	v_add_f32_e32 v64, 1.0, v64
	v_pk_mul_f32 v[50:51], v[58:59], v[50:51]
	v_add_f32_e32 v65, 1.0, v65
	v_pk_mul_f32 v[58:59], v[50:51], v[60:61]
	v_fmamk_f32 v50, v140, 0x3a800000, v221
	v_rsq_f32_e32 v60, v50
	v_rcp_f32_e32 v64, v64
	v_rcp_f32_e32 v65, v65
	v_add_u32_e32 v61, s0, v77
	v_pk_mul_f32 v[46:47], v[46:47], v[60:61] op_sel_hi:[1,0]
	v_cvt_pk_bf16_f32 v50, v54, v55
	v_pk_mul_f32 v[56:57], v[56:57], v[64:65]
	v_mul_f32_e32 v52, 0xbfb8aa3b, v46
	v_lshlrev_b32_e32 v64, 1, v61
	v_cvt_pk_bf16_f32 v51, v56, v57
	v_exp_f32_e32 v54, v52
	v_cvt_pk_bf16_f32 v52, v62, v63
	v_cvt_pk_bf16_f32 v53, v58, v59
	buffer_store_dwordx4 v[50:53], v64, s[20:23], 0 offen sc1
	v_pk_mul_f32 v[38:39], v[38:39], v[60:61] op_sel_hi:[1,0]
	v_pk_mul_f32 v[42:43], v[42:43], v[60:61] op_sel_hi:[1,0]
	v_mul_f32_e32 v51, 0xbfb8aa3b, v47
	v_exp_f32_e32 v51, v51
	v_add_f32_e32 v50, 1.0, v54
	v_pk_mul_f32 v[38:39], v[46:47], v[38:39]
	v_rcp_f32_e32 v50, v50
	v_add_f32_e32 v46, 1.0, v51
	v_rcp_f32_e32 v51, v46
	v_pk_mul_f32 v[46:47], v[48:49], v[60:61] op_sel_hi:[1,0]
	v_pk_mul_f32 v[40:41], v[40:41], v[60:61] op_sel_hi:[1,0]
	v_mul_f32_e32 v49, 0xbfb8aa3b, v47
	v_pk_mul_f32 v[38:39], v[38:39], v[50:51]
	v_mul_f32_e32 v50, 0xbfb8aa3b, v42
	v_pk_mul_f32 v[40:41], v[46:47], v[40:41]
	v_mul_f32_e32 v47, 0xbfb8aa3b, v43
	v_pk_mul_f32 v[34:35], v[34:35], v[60:61] op_sel_hi:[1,0]
	v_exp_f32_e32 v50, v50
	v_exp_f32_e32 v47, v47
	v_pk_mul_f32 v[34:35], v[42:43], v[34:35]
	v_pk_mul_f32 v[42:43], v[44:45], v[60:61] op_sel_hi:[1,0]
	v_mul_f32_e32 v48, 0xbfb8aa3b, v46
	v_mul_f32_e32 v44, 0xbfb8aa3b, v42
	v_mul_f32_e32 v45, 0xbfb8aa3b, v43
	v_exp_f32_e32 v44, v44
	v_exp_f32_e32 v45, v45
	v_add_f32_e32 v46, 1.0, v50
	v_add_f32_e32 v47, 1.0, v47
	v_rcp_f32_e32 v46, v46
	v_rcp_f32_e32 v47, v47
	v_add_f32_e32 v44, 1.0, v44
	v_add_f32_e32 v45, 1.0, v45
	v_rcp_f32_e32 v44, v44
	v_rcp_f32_e32 v45, v45
	v_exp_f32_e32 v48, v48
	v_exp_f32_e32 v49, v49
	v_pk_mul_f32 v[46:47], v[34:35], v[46:47]
	v_pk_mul_f32 v[34:35], v[36:37], v[60:61] op_sel_hi:[1,0]
	v_add_f32_e32 v48, 1.0, v48
	v_pk_mul_f32 v[34:35], v[42:43], v[34:35]
	v_add_f32_e32 v49, 1.0, v49
	v_pk_mul_f32 v[42:43], v[34:35], v[44:45]
	v_fmamk_f32 v34, v131, 0x3a800000, v221
	v_rsq_f32_e32 v44, v34
	v_rcp_f32_e32 v48, v48
	v_rcp_f32_e32 v49, v49
	v_add_u32_e32 v45, s53, v61
	v_pk_mul_f32 v[30:31], v[30:31], v[44:45] op_sel_hi:[1,0]
	v_cvt_pk_bf16_f32 v34, v38, v39
	v_pk_mul_f32 v[40:41], v[40:41], v[48:49]
	v_mul_f32_e32 v36, 0xbfb8aa3b, v30
	v_lshlrev_b32_e32 v48, 1, v45
	v_cvt_pk_bf16_f32 v35, v40, v41
	v_exp_f32_e32 v38, v36
	v_cvt_pk_bf16_f32 v36, v46, v47
	v_cvt_pk_bf16_f32 v37, v42, v43
	buffer_store_dwordx4 v[34:37], v48, s[20:23], 0 offen sc1
	v_pk_mul_f32 v[22:23], v[22:23], v[44:45] op_sel_hi:[1,0]
	v_pk_mul_f32 v[26:27], v[26:27], v[44:45] op_sel_hi:[1,0]
	v_mul_f32_e32 v35, 0xbfb8aa3b, v31
	v_exp_f32_e32 v35, v35
	v_add_f32_e32 v34, 1.0, v38
	v_pk_mul_f32 v[22:23], v[30:31], v[22:23]
	v_rcp_f32_e32 v34, v34
	v_add_f32_e32 v30, 1.0, v35
	v_rcp_f32_e32 v35, v30
	v_pk_mul_f32 v[30:31], v[32:33], v[44:45] op_sel_hi:[1,0]
	v_pk_mul_f32 v[24:25], v[24:25], v[44:45] op_sel_hi:[1,0]
	v_mul_f32_e32 v33, 0xbfb8aa3b, v31
	v_pk_mul_f32 v[22:23], v[22:23], v[34:35]
	v_mul_f32_e32 v34, 0xbfb8aa3b, v26
	v_pk_mul_f32 v[24:25], v[30:31], v[24:25]
	v_mul_f32_e32 v31, 0xbfb8aa3b, v27
	v_pk_mul_f32 v[18:19], v[18:19], v[44:45] op_sel_hi:[1,0]
	v_exp_f32_e32 v34, v34
	v_exp_f32_e32 v31, v31
	v_pk_mul_f32 v[18:19], v[26:27], v[18:19]
	v_pk_mul_f32 v[26:27], v[28:29], v[44:45] op_sel_hi:[1,0]
	v_mul_f32_e32 v32, 0xbfb8aa3b, v30
	v_mul_f32_e32 v28, 0xbfb8aa3b, v26
	v_mul_f32_e32 v29, 0xbfb8aa3b, v27
	v_exp_f32_e32 v28, v28
	v_exp_f32_e32 v29, v29
	v_add_f32_e32 v30, 1.0, v34
	v_add_f32_e32 v31, 1.0, v31
	v_rcp_f32_e32 v30, v30
	v_rcp_f32_e32 v31, v31
	v_add_f32_e32 v28, 1.0, v28
	v_add_f32_e32 v29, 1.0, v29
	v_rcp_f32_e32 v28, v28
	v_rcp_f32_e32 v29, v29
	v_exp_f32_e32 v32, v32
	v_exp_f32_e32 v33, v33
	v_pk_mul_f32 v[30:31], v[18:19], v[30:31]
	v_pk_mul_f32 v[18:19], v[20:21], v[44:45] op_sel_hi:[1,0]
	v_add_f32_e32 v32, 1.0, v32
	v_pk_mul_f32 v[18:19], v[26:27], v[18:19]
	v_add_f32_e32 v33, 1.0, v33
	v_pk_mul_f32 v[26:27], v[18:19], v[28:29]
	v_fmamk_f32 v18, v130, 0x3a800000, v221
	v_rsq_f32_e32 v28, v18
	v_rcp_f32_e32 v32, v32
	v_rcp_f32_e32 v33, v33
	v_add_u32_e32 v29, s53, v45
	v_pk_mul_f32 v[14:15], v[14:15], v[28:29] op_sel_hi:[1,0]
	v_cvt_pk_bf16_f32 v18, v22, v23
	v_pk_mul_f32 v[24:25], v[24:25], v[32:33]
	v_mul_f32_e32 v20, 0xbfb8aa3b, v14
	v_lshlrev_b32_e32 v32, 1, v29
	v_cvt_pk_bf16_f32 v19, v24, v25
	v_exp_f32_e32 v22, v20
	v_cvt_pk_bf16_f32 v20, v30, v31
	v_cvt_pk_bf16_f32 v21, v26, v27
	buffer_store_dwordx4 v[18:21], v32, s[20:23], 0 offen sc1
	v_pk_mul_f32 v[6:7], v[6:7], v[28:29] op_sel_hi:[1,0]
	v_pk_mul_f32 v[10:11], v[10:11], v[28:29] op_sel_hi:[1,0]
	v_mul_f32_e32 v19, 0xbfb8aa3b, v15
	v_exp_f32_e32 v19, v19
	v_add_f32_e32 v18, 1.0, v22
	v_pk_mul_f32 v[6:7], v[14:15], v[6:7]
	v_rcp_f32_e32 v18, v18
	v_add_f32_e32 v14, 1.0, v19
	v_rcp_f32_e32 v19, v14
	v_pk_mul_f32 v[14:15], v[16:17], v[28:29] op_sel_hi:[1,0]
	v_pk_mul_f32 v[8:9], v[8:9], v[28:29] op_sel_hi:[1,0]
	v_mul_f32_e32 v17, 0xbfb8aa3b, v15
	v_pk_mul_f32 v[6:7], v[6:7], v[18:19]
	v_mul_f32_e32 v18, 0xbfb8aa3b, v10
	v_pk_mul_f32 v[8:9], v[14:15], v[8:9]
	v_mul_f32_e32 v15, 0xbfb8aa3b, v11
	v_pk_mul_f32 v[2:3], v[2:3], v[28:29] op_sel_hi:[1,0]
	v_exp_f32_e32 v18, v18
	v_exp_f32_e32 v15, v15
	v_pk_mul_f32 v[2:3], v[10:11], v[2:3]
	v_pk_mul_f32 v[10:11], v[12:13], v[28:29] op_sel_hi:[1,0]
	v_mul_f32_e32 v16, 0xbfb8aa3b, v14
	v_mul_f32_e32 v12, 0xbfb8aa3b, v10
	v_mul_f32_e32 v13, 0xbfb8aa3b, v11
	v_exp_f32_e32 v16, v16
	v_exp_f32_e32 v17, v17
	v_exp_f32_e32 v12, v12
	v_exp_f32_e32 v13, v13
	v_add_f32_e32 v14, 1.0, v18
	v_add_f32_e32 v15, 1.0, v15
	v_rcp_f32_e32 v14, v14
	v_rcp_f32_e32 v15, v15
	v_add_f32_e32 v16, 1.0, v16
	v_add_f32_e32 v17, 1.0, v17
	v_add_f32_e32 v12, 1.0, v12
	v_add_f32_e32 v13, 1.0, v13
	v_rcp_f32_e32 v16, v16
	v_rcp_f32_e32 v17, v17
	v_rcp_f32_e32 v12, v12
	v_rcp_f32_e32 v13, v13
	v_pk_mul_f32 v[14:15], v[2:3], v[14:15]
	v_pk_mul_f32 v[2:3], v[4:5], v[28:29] op_sel_hi:[1,0]
	v_pk_mul_f32 v[8:9], v[8:9], v[16:17]
	v_pk_mul_f32 v[2:3], v[10:11], v[2:3]
	v_cvt_pk_bf16_f32 v4, v14, v15
	v_pk_mul_f32 v[10:11], v[2:3], v[12:13]
	v_add_lshl_u32 v12, v29, s53, 1
	v_cvt_pk_bf16_f32 v2, v6, v7
	v_cvt_pk_bf16_f32 v3, v8, v9
	v_cvt_pk_bf16_f32 v5, v10, v11
	buffer_store_dwordx4 v[2:5], v12, s[20:23], 0 offen sc1
.Lhu_epi_tail:
	s_and_b64 vcc, exec, s[40:41]
	s_mov_b64 s[34:35], -1
	s_cbranch_vccnz .LBB0_161
	s_branch .LBB0_225
.LBB0_174:
	v_lshl_add_u32 v198, s99, 8, v1
	s_cmp_eq_u32 s101, 2
	s_cselect_b32 s0, 0x80, 0
	v_add_u32_e32 v198, s0, v198
	s_cmp_lt_i32 s70, 1
	s_mov_b64 s[34:35], -1
	s_cbranch_scc1 .LBB0_172
